# v7 + P7 bonus/attention-output loads hoisted next to the y/g loads + P0 XN loop in 4-row batches
# baseline (speedup 1.0000x reference)
.LBB0_1432:
	v_lshl_add_u64 v[26:27], s[26:27], 0, v[74:75]
	v_add_co_u32_e32 v46, vcc, 0x2bf00000, v26
	v_lshl_add_u64 v[42:43], v[26:27], 0, s[14:15]
	s_nop 0
	v_addc_co_u32_e32 v47, vcc, 0, v27, vcc
	v_add_co_u32_e32 v48, vcc, 0x29e00000, v26
	v_lshl_add_u64 v[44:45], v[26:27], 0, s[16:17]
	s_nop 0
	v_addc_co_u32_e32 v49, vcc, 0, v27, vcc
	global_load_dwordx4 v[38:41], v[46:47], off
	global_load_dwordx4 v[34:37], v[48:49], off
	global_load_dwordx4 v[30:33], v[42:43], off offset:16
	global_load_dwordx4 v[26:29], v[44:45], off offset:16
	v_lshl_add_u64 v[170:171], s[26:27], 0, v[78:79]
	global_load_dword v172, v[170:171], off
	v_lshl_add_u64 v[174:175], s[26:27], 0, v[76:77]
	v_add_co_u32_e32 v174, vcc, 0x2e000000, v174
	s_nop 1
	v_addc_co_u32_e32 v175, vcc, 0, v175, vcc
	global_load_dwordx4 v[176:179], v[174:175], off
	global_load_dwordx4 v[180:183], v[174:175], off offset:256
	s_mov_b64 s[18:19], -1
	s_and_b64 vcc, exec, s[0:1]
	s_cbranch_vccz .LBB0_1434
	v_lshl_add_u64 v[50:51], v[50:51], 2, v[66:67]
	global_load_dwordx4 v[42:45], v[50:51], off offset:1296
	global_load_dwordx4 v[46:49], v[50:51], off offset:1280
	s_mov_b64 s[18:19], 0
.LBB0_1434:
	s_andn2_b64 vcc, exec, s[18:19]
	s_cbranch_vccnz .LBB0_1436
	s_ashr_i32 s0, s2, 8
	s_and_b32 s0, s0, -8
	s_waitcnt vmcnt(4)
	v_add_u32_e32 v42, s0, v60
	v_ashrrev_i32_e32 v43, 31, v42
	v_lshlrev_b64 v[42:43], 7, v[42:43]
	s_bfe_u32 s0, s2, 0x70004
	v_or_b32_e32 v42, s0, v42
	v_mov_b64_e32 v[44:45], s[6:7]
	v_mad_u64_u32 v[44:45], s[0:1], v42, s5, v[44:45]
	s_and_b32 s0, s25, 0x3c0
	s_nop 0
	v_or_b32_e32 v42, s0, v62
	v_mad_i32_i24 v45, v43, s5, v45
	v_lshlrev_b32_e32 v58, 1, v42
	v_lshl_add_u64 v[42:43], v[44:45], 0, v[58:59]
	v_add_co_u32_e32 v42, vcc, s28, v42
	s_nop 1
	v_addc_co_u32_e32 v43, vcc, 0, v43, vcc
	global_load_dwordx4 v[42:45], v[42:43], off offset:2304
	s_waitcnt vmcnt(0)
	v_lshlrev_b32_e32 v46, 16, v42
	v_and_b32_e32 v47, 0xffff0000, v42
	v_lshlrev_b32_e32 v48, 16, v43
	v_and_b32_e32 v49, 0xffff0000, v43
	v_lshlrev_b32_e32 v42, 16, v44
	v_and_b32_e32 v43, 0xffff0000, v44
	v_lshlrev_b32_e32 v44, 16, v45
	v_and_b32_e32 v45, 0xffff0000, v45
.LBB0_1436:
	s_waitcnt vmcnt(4)
	v_mov_b32_e32 v52, v39
	v_mov_b32_e32 v53, v40
	v_mov_b32_e32 v54, v38
	v_mov_b32_e32 v55, v41
	v_pk_add_f32 v[52:53], v[52:53], v[54:55]
	s_waitcnt vmcnt(2)
	v_mov_b32_e32 v54, v32
	v_mov_b32_e32 v55, v30
	v_mov_b32_e32 v56, v33
	v_mov_b32_e32 v57, v31
	v_pk_add_f32 v[54:55], v[54:55], v[56:57]
	v_add_f32_e32 v51, v52, v53
	v_add_f32_e32 v51, v51, v55
	v_add_f32_e32 v51, v54, v51
	s_cmpk_lt_i32 s2, 0x4000
	s_nop 0
	v_add_f32_dpp v51, v51, v51 quad_perm:[1,0,3,2] row_mask:0xf bank_mask:0xf bound_ctrl:1
	s_nop 1
	v_add_f32_dpp v51, v51, v51 quad_perm:[2,3,0,1] row_mask:0xf bank_mask:0xf bound_ctrl:1
	s_nop 1
	v_add_f32_dpp v51, v51, v51 row_half_mirror row_mask:0xf bank_mask:0xf bound_ctrl:1
	v_fmamk_f32 v39, v51, 0xbc800000, v39
	v_fmamk_f32 v38, v51, 0xbc800000, v38
	v_fmamk_f32 v41, v51, 0xbc800000, v41
	v_fmac_f32_e32 v40, 0xbc800000, v51
	v_pk_mul_f32 v[52:53], v[40:41], v[40:41]
	v_pk_mul_f32 v[54:55], v[38:39], v[38:39]
	v_fmamk_f32 v31, v51, 0xbc800000, v31
	v_fmamk_f32 v30, v51, 0xbc800000, v30
	v_fmamk_f32 v33, v51, 0xbc800000, v33
	v_fmac_f32_e32 v32, 0xbc800000, v51
	v_pk_mov_b32 v[56:57], v[54:55], v[52:53] op_sel:[1,0]
	v_mov_b32_e32 v55, v53
	v_pk_add_f32 v[52:53], v[56:57], v[54:55]
	v_pk_mul_f32 v[54:55], v[32:33], v[32:33]
	v_pk_mul_f32 v[56:57], v[30:31], v[30:31]
	v_mov_b32_e32 v82, v54
	v_mov_b32_e32 v83, v56
	v_mov_b32_e32 v56, v55
	v_pk_add_f32 v[54:55], v[82:83], v[56:57]
	v_add_f32_e32 v51, v52, v53
	v_add_f32_e32 v51, v55, v51
	v_add_f32_e32 v51, v54, v51
	v_lshl_add_u64 v[82:83], s[26:27], 0, v[72:73]
	s_nop 0
	v_add_f32_dpp v51, v51, v51 quad_perm:[1,0,3,2] row_mask:0xf bank_mask:0xf bound_ctrl:1
	s_nop 1
	v_add_f32_dpp v51, v51, v51 quad_perm:[2,3,0,1] row_mask:0xf bank_mask:0xf bound_ctrl:1
	s_nop 1
	v_add_f32_dpp v51, v51, v51 row_half_mirror row_mask:0xf bank_mask:0xf bound_ctrl:1
	v_fmamk_f32 v51, v51, 0x3c800000, v61
	v_mul_f32_e32 v52, 0x4f800000, v51
	v_cmp_gt_f32_e32 vcc, s30, v51
	s_nop 1
	v_cndmask_b32_e32 v51, v51, v52, vcc
	v_sqrt_f32_e32 v52, v51
	s_nop 0
	v_add_u32_e32 v53, -1, v52
	v_add_u32_e32 v54, 1, v52
	v_fma_f32 v55, -v53, v52, v51
	v_fma_f32 v56, -v54, v52, v51
	v_cmp_ge_f32_e64 s[0:1], 0, v55
	s_nop 1
	v_cndmask_b32_e64 v52, v52, v53, s[0:1]
	v_cmp_lt_f32_e64 s[0:1], 0, v56
	s_nop 1
	v_cndmask_b32_e64 v52, v52, v54, s[0:1]
	v_mul_f32_e32 v53, 0x37800000, v52
	v_cndmask_b32_e32 v52, v52, v53, vcc
	v_cmp_class_f32_e32 vcc, v51, v63
	s_nop 1
	v_cndmask_b32_e32 v51, v52, v51, vcc
	v_div_scale_f32 v52, s[0:1], v51, v51, 1.0
	v_rcp_f32_e32 v53, v52
	v_div_scale_f32 v54, vcc, 1.0, v51, 1.0
	s_mov_b64 s[0:1], -1
	v_fma_f32 v55, -v52, v53, 1.0
	v_fmac_f32_e32 v53, v55, v53
	v_mul_f32_e32 v55, v54, v53
	v_fma_f32 v56, -v52, v55, v54
	v_fmac_f32_e32 v55, v56, v53
	v_fma_f32 v52, -v52, v55, v54
	v_div_fmas_f32 v52, v52, v53, v55
	v_div_fixup_f32 v52, v52, v51, 1.0
	v_pk_mul_f32 v[38:39], v[38:39], v[52:53] op_sel_hi:[1,0]
	v_pk_mul_f32 v[30:31], v[30:31], v[52:53] op_sel_hi:[1,0]
	v_pk_fma_f32 v[38:39], v[14:15], v[38:39], v[22:23]
	v_pk_mul_f32 v[32:33], v[32:33], v[52:53] op_sel_hi:[1,0]
	s_waitcnt vmcnt(0)
	v_pk_fma_f32 v[38:39], v[46:47], v[172:173], v[38:39] op_sel_hi:[1,0,1]
	v_pk_fma_f32 v[32:33], v[12:13], v[32:33], v[20:21]
	v_pk_fma_f32 v[30:31], v[10:11], v[30:31], v[18:19]
	v_pk_mul_f32 v[40:41], v[40:41], v[52:53] op_sel_hi:[1,0]
	v_pk_mul_f32 v[34:35], v[34:35], v[38:39]
	v_pk_fma_f32 v[30:31], v[42:43], v[172:173], v[30:31] op_sel_hi:[1,0,1]
	v_pk_fma_f32 v[32:33], v[44:45], v[172:173], v[32:33] op_sel_hi:[1,0,1]
	v_pk_fma_f32 v[40:41], v[16:17], v[40:41], v[24:25]
	v_pk_mul_f32 v[32:33], v[28:29], v[32:33]
	v_pk_mul_f32 v[28:29], v[26:27], v[30:31]
	v_bfe_u32 v26, v34, 16, 1
	v_pk_fma_f32 v[40:41], v[48:49], v[172:173], v[40:41] op_sel_hi:[1,0,1]
	v_add3_u32 v26, v34, v26, s31
	v_bfe_u32 v27, v35, 16, 1
	v_pk_mul_f32 v[36:37], v[36:37], v[40:41]
	v_lshrrev_b32_e32 v26, 16, v26
	v_add3_u32 v27, v35, v27, s31
	v_and_or_b32 v26, v27, s29, v26
	v_bfe_u32 v27, v36, 16, 1
	v_add3_u32 v27, v36, v27, s31
	v_bfe_u32 v30, v37, 16, 1
	v_lshrrev_b32_e32 v27, 16, v27
	v_add3_u32 v30, v37, v30, s31
	v_and_or_b32 v27, v30, s29, v27
	v_bfe_u32 v30, v28, 16, 1
	v_add3_u32 v28, v28, v30, s31
	v_bfe_u32 v30, v29, 16, 1
	v_lshrrev_b32_e32 v28, 16, v28
	v_add3_u32 v29, v29, v30, s31
	v_and_or_b32 v28, v29, s29, v28
	v_bfe_u32 v29, v32, 16, 1
	v_add3_u32 v29, v32, v29, s31
	v_bfe_u32 v30, v33, 16, 1
	v_lshrrev_b32_e32 v29, 16, v29
	v_add3_u32 v30, v33, v30, s31
	v_and_or_b32 v29, v30, s29, v29
	v_add_co_u32_e32 v30, vcc, 0x30000000, v82
	s_nop 1
	v_addc_co_u32_e32 v31, vcc, 0, v83, vcc
	global_store_dwordx4 v[30:31], v[26:29], off
	s_cbranch_scc0 .LBB0_1438
	s_nop 0
	s_mov_b64 s[0:1], 0
	v_lshlrev_b32_e32 v34, 16, v176
	v_and_b32_e32 v35, 0xffff0000, v176
	v_lshlrev_b32_e32 v36, 16, v180
	v_and_b32_e32 v37, 0xffff0000, v180
	v_lshlrev_b32_e32 v26, 16, v177
	v_and_b32_e32 v27, 0xffff0000, v177
	v_lshlrev_b32_e32 v30, 16, v181
	v_and_b32_e32 v31, 0xffff0000, v181
	v_lshlrev_b32_e32 v38, 16, v178
	v_and_b32_e32 v39, 0xffff0000, v178
	v_lshlrev_b32_e32 v40, 16, v182
	v_and_b32_e32 v41, 0xffff0000, v182
	v_lshlrev_b32_e32 v28, 16, v179
	v_and_b32_e32 v29, 0xffff0000, v179
	v_lshlrev_b32_e32 v42, 16, v183
	v_and_b32_e32 v43, 0xffff0000, v183
	v_pk_fma_f32 v[36:37], v[70:71], v[36:37], v[34:35] neg_lo:[1,0,0] neg_hi:[1,0,0]
	v_pk_fma_f32 v[32:33], v[70:71], v[30:31], v[26:27] neg_lo:[1,0,0] neg_hi:[1,0,0]
	v_pk_fma_f32 v[26:27], v[70:71], v[40:41], v[38:39] neg_lo:[1,0,0] neg_hi:[1,0,0]
	v_pk_fma_f32 v[28:29], v[70:71], v[42:43], v[28:29] neg_lo:[1,0,0] neg_hi:[1,0,0]
	v_mov_b32_e32 v34, v36
	v_mov_b32_e32 v35, v32
	v_mov_b32_e32 v38, v37
	v_mov_b32_e32 v39, v33
	v_mov_b32_e32 v40, v28
	v_mov_b32_e32 v41, v26
	v_pk_mul_f32 v[34:35], v[34:35], v[34:35]
	v_mov_b32_e32 v42, v29
	v_mov_b32_e32 v43, v27
	v_pk_mul_f32 v[40:41], v[40:41], v[40:41]
	v_pk_fma_f32 v[34:35], v[38:39], v[38:39], v[34:35]
	v_mov_b32_e32 v31, v32
	v_pk_fma_f32 v[38:39], v[42:43], v[42:43], v[40:41]
	v_add_f32_e32 v32, v34, v35
	v_add_f32_e32 v32, v39, v32
	v_add_f32_e32 v32, v38, v32
	v_mov_b32_e32 v30, v36
	s_nop 0
	v_add_f32_dpp v32, v32, v32 quad_perm:[1,0,3,2] row_mask:0xf bank_mask:0xf bound_ctrl:1
	s_nop 1
	v_add_f32_dpp v32, v32, v32 quad_perm:[2,3,0,1] row_mask:0xf bank_mask:0xf bound_ctrl:1
	s_nop 1
	v_add_f32_dpp v34, v32, v32 row_half_mirror row_mask:0xf bank_mask:0xf bound_ctrl:1
	v_mov_b32_e32 v32, v37
	s_nop 0
	v_mov_b32_dpp v35, v34 row_mirror row_mask:0xf bank_mask:0xf bound_ctrl:1
